# FFN-out/Wo GEMM K-loop first iteration peeled too (C=0 MFMAs, no accumulator zeroing), on top of the FFN-in peel
# baseline (speedup 1.0000x reference)
; #define PG8_STAGE(bufoff, gbase, voff) do { _Pragma("unroll") for (int _i = 0; _i < 2; ++_i) \
;         __builtin_amdgcn_global_load_lds((const unsigned*)((const char*)(gbase) + (voff)[_i]), (PG8_LAS unsigned*)(lds + (bufoff) + ldsw + _i * 8192), 16, 0, 0); } while (0)
; #define PG8_LDA(dst, b, h) do { _Pragma("unroll") for (int m = 0; m < 4; ++m) _Pragma("unroll") for (int k = 0; k < 2; ++k) dst[m][k] = *(const PG8_LAS bf16x8*)(lds + PG8_SA(b, h) + aoff + m * 2048 + k * 1024); } while (0)
; #define PG8_LDB(dst, b, h) do { _Pragma("unroll") for (int n = 0; n < 2; ++n) _Pragma("unroll") for (int k = 0; k < 2; ++k) dst[n][k] = *(const PG8_LAS bf16x8*)(lds + PG8_SB(b, h) + boff + n * 2048 + k * 1024); } while (0)
; #define PG8_MMA(ai, bj, At, Bt) do { __builtin_amdgcn_s_setprio(1); _Pragma("unroll") for (int m = 0; m < 4; ++m) _Pragma("unroll") for (int n = 0; n < 2; ++n) _Pragma("unroll") for (int k = 0; k < 2; ++k) \
;         acc[ai][bj][m][n] = __builtin_amdgcn_mfma_f32_16x16x32_bf16(Bt[n][k], At[m][k], acc[ai][bj][m][n], 0, 0, 0); __builtin_amdgcn_s_setprio(0); } while (0)
; #define PG8_WAIT_V(n) asm volatile("s_waitcnt vmcnt(" #n ")" ::: "memory")
; #define PG8_WAIT_L(n) asm volatile("s_waitcnt lgkmcnt(" #n ")" ::: "memory")
; #define PG8_BAR __builtin_amdgcn_s_barrier()
; template <class Epi, class Sched, bool ALIGN_EPI = false, bool SP2 = false>
; __device__ __forceinline__ void gemm_phase(PG8_LAS unsigned char* lds, const Gemm g, const Sched& S, const Epi& E, const int tid_in) {
;     ...
;         const int nt = cur.nt;
;         for (int t = 0; t < nt; t += 2) {
;             const bool last = (t == nt - 2);
;             const char* a1 = cA + (size_t)(t + 1) * kstep;
;             const char* a2 = last ? nA : cA + (size_t)(t + 2) * kstep; const char* b2 = last ? nB : cB + (size_t)(t + 2) * kstep;
;             const char* a3 = a2 + kstep; const char* b3 = b2 + kstep;
;             if (last && has_next) S.a_ready(nxt);
;             if constexpr (SP2) {
;             PG8_LDB(B0, 0, 0); PG8_LDB(B1, 0, 1); PG8_SCHED; PG8_LDA(At, 0, 0); PG8_STAGE(PG8_SA(1, 1), a1 + hstep, voffA);
;             PG8_WAIT_V(8); PG8_WAIT_L(0); PG8_BAR; PG8_MMA(0, 0, At, B0); PG8_MMA(0, 1, At, B1); PG8_BAR; PG8_SCHED;
;             PG8_LDA(At, 0, 1); PG8_STAGE(PG8_SB(0, 0), b2, voffB); PG8_STAGE(PG8_SB(0, 1), b2 + hstep, voffB); PG8_STAGE(PG8_SA(0, 0), a2, voffA);
.LBB0_282:
	s_cmp_eq_u32 s50, 0
	s_cbranch_scc1 .LBB0_294
	s_add_i32 s28, s50, -2
	s_add_u32 s24, s24, 0x80
	s_addc_u32 s25, s25, 0
	s_add_u32 s29, s26, 0x100
	s_addc_u32 s51, s27, 0
	s_mov_b32 s26, 0
	s_add_i32 s52, s26, 2
	s_add_u32 s53, s24, 0x80
	s_addc_u32 s27, s25, 0
	s_add_i32 s56, 0, 0x10000
	s_cmp_eq_u32 s28, s26
	s_cselect_b32 s27, s21, s27
	s_cselect_b32 s26, s20, s53
	s_cselect_b32 s55, s23, s51
	s_cselect_b32 s54, s22, s29
	s_add_i32 s53, 0, 0x14000
	v_add_u32_e32 v154, s56, v143
	v_add_u32_e32 v170, s53, v143
	ds_read_b128 v[138:141], v154
	ds_read_b128 v[146:149], v154 offset:1024
	ds_read_b128 v[150:153], v154 offset:2048
	ds_read_b128 v[154:157], v154 offset:3072
	ds_read_b128 v[158:161], v170
	ds_read_b128 v[162:165], v170 offset:1024
	ds_read_b128 v[166:169], v170 offset:2048
	ds_read_b128 v[170:173], v170 offset:3072
	v_lshl_add_u64 v[190:191], s[24:25], 0, v[134:135]
	s_add_i32 m0, s38, 0xc000
	ds_read_b128 v[174:177], v145
	ds_read_b128 v[178:181], v145 offset:1024
	ds_read_b128 v[182:185], v145 offset:2048
	ds_read_b128 v[186:189], v145 offset:3072
	ds_read_b128 v[200:203], v145 offset:4096
	ds_read_b128 v[204:207], v145 offset:5120
	ds_read_b128 v[208:211], v145 offset:6144
	ds_read_b128 v[212:215], v145 offset:7168
	global_load_lds_dwordx4 v[190:191], off
	v_lshl_add_u64 v[190:191], s[24:25], 0, v[136:137]
	s_add_i32 m0, s38, 0xe000
	s_nop 0
	global_load_lds_dwordx4 v[190:191], off
	s_waitcnt vmcnt(8)
	s_waitcnt lgkmcnt(0)
	s_barrier
	s_setprio 1
	s_waitcnt lgkmcnt(0)
	v_mfma_f32_16x16x32_bf16 v[124:127], v[138:141], v[174:177], 0
	v_mfma_f32_16x16x32_bf16 v[120:123], v[150:153], v[174:177], 0
	v_mfma_f32_16x16x32_bf16 v[108:111], v[138:141], v[182:185], 0
	v_mfma_f32_16x16x32_bf16 v[104:107], v[150:153], v[182:185], 0
	v_mfma_f32_16x16x32_bf16 v[92:95], v[138:141], v[200:203], 0
	v_mfma_f32_16x16x32_bf16 v[88:91], v[150:153], v[200:203], 0
	v_mfma_f32_16x16x32_bf16 v[76:79], v[138:141], v[208:211], 0
	v_mfma_f32_16x16x32_bf16 v[72:75], v[150:153], v[208:211], 0
	v_mfma_f32_16x16x32_bf16 v[124:127], v[146:149], v[178:181], v[124:127]
	v_mfma_f32_16x16x32_bf16 v[120:123], v[154:157], v[178:181], v[120:123]
	v_mfma_f32_16x16x32_bf16 v[108:111], v[146:149], v[186:189], v[108:111]
	v_mfma_f32_16x16x32_bf16 v[104:107], v[154:157], v[186:189], v[104:107]
	v_mfma_f32_16x16x32_bf16 v[92:95], v[146:149], v[204:207], v[92:95]
	v_mfma_f32_16x16x32_bf16 v[88:91], v[154:157], v[204:207], v[88:91]
	v_mfma_f32_16x16x32_bf16 v[76:79], v[146:149], v[212:215], v[76:79]
	v_mfma_f32_16x16x32_bf16 v[72:75], v[154:157], v[212:215], v[72:75]
	s_setprio 0
	s_setprio 1
	v_mfma_f32_16x16x32_bf16 v[116:119], v[158:161], v[174:177], 0
	v_mfma_f32_16x16x32_bf16 v[112:115], v[166:169], v[174:177], 0
	v_mfma_f32_16x16x32_bf16 v[100:103], v[158:161], v[182:185], 0
	v_mfma_f32_16x16x32_bf16 v[96:99], v[166:169], v[182:185], 0
	v_mfma_f32_16x16x32_bf16 v[84:87], v[158:161], v[200:203], 0
	v_mfma_f32_16x16x32_bf16 v[80:83], v[166:169], v[200:203], 0
	v_mfma_f32_16x16x32_bf16 v[68:71], v[158:161], v[208:211], 0
	v_mfma_f32_16x16x32_bf16 v[64:67], v[166:169], v[208:211], 0
	v_mfma_f32_16x16x32_bf16 v[116:119], v[162:165], v[178:181], v[116:119]
	v_mfma_f32_16x16x32_bf16 v[112:115], v[170:173], v[178:181], v[112:115]
	v_mfma_f32_16x16x32_bf16 v[100:103], v[162:165], v[186:189], v[100:103]
	v_mfma_f32_16x16x32_bf16 v[96:99], v[170:173], v[186:189], v[96:99]
	v_mfma_f32_16x16x32_bf16 v[84:87], v[162:165], v[204:207], v[84:87]
	v_mfma_f32_16x16x32_bf16 v[80:83], v[170:173], v[204:207], v[80:83]
	v_mfma_f32_16x16x32_bf16 v[68:71], v[162:165], v[212:215], v[68:71]
	v_mfma_f32_16x16x32_bf16 v[64:67], v[170:173], v[212:215], v[64:67]
	s_setprio 0
	s_barrier
	s_add_i32 s56, s56, s35
	v_lshl_add_u64 v[190:191], s[54:55], 0, v[192:193]
	s_mov_b32 m0, s56
	ds_read_b128 v[174:177], v145 offset:16384
	ds_read_b128 v[178:181], v145 offset:17408
	ds_read_b128 v[182:185], v145 offset:18432
	ds_read_b128 v[186:189], v145 offset:19456
	ds_read_b128 v[200:203], v145 offset:20480
	ds_read_b128 v[204:207], v145 offset:21504
	ds_read_b128 v[208:211], v145 offset:22528
	ds_read_b128 v[212:215], v145 offset:23552
	global_load_lds_dwordx4 v[190:191], off
	s_add_i32 m0, s56, 0x2000
	v_lshl_add_u64 v[218:219], s[54:55], 0, v[132:133]
	s_add_u32 s54, s54, s12
	s_addc_u32 s55, s55, 0
	s_add_i32 s53, s53, s35
	global_load_lds_dwordx4 v[218:219], off
	v_lshl_add_u64 v[220:221], s[54:55], 0, v[192:193]
	s_mov_b32 m0, s53
	v_lshl_add_u64 v[230:231], s[54:55], 0, v[132:133]
	global_load_lds_dwordx4 v[220:221], off
	s_add_i32 m0, s53, 0x2000
	v_lshl_add_u64 v[232:233], s[26:27], 0, v[128:129]
	global_load_lds_dwordx4 v[230:231], off
	s_mov_b32 m0, s38
	v_lshl_add_u64 v[234:235], s[26:27], 0, v[130:131]
	global_load_lds_dwordx4 v[232:233], off
	s_mov_b32 m0, s39
	s_nop 0
	global_load_lds_dwordx4 v[234:235], off
	s_waitcnt vmcnt(8)
	s_waitcnt lgkmcnt(0)
	s_barrier
; #define PG8_STAGE(bufoff, gbase, voff) do { _Pragma("unroll") for (int _i = 0; _i < 2; ++_i) \
;         __builtin_amdgcn_global_load_lds((const unsigned*)((const char*)(gbase) + (voff)[_i]), (PG8_LAS unsigned*)(lds + (bufoff) + ldsw + _i * 8192), 16, 0, 0); } while (0)
; #define PG8_LDA(dst, b, h) do { _Pragma("unroll") for (int m = 0; m < 4; ++m) _Pragma("unroll") for (int k = 0; k < 2; ++k) dst[m][k] = *(const PG8_LAS bf16x8*)(lds + PG8_SA(b, h) + aoff + m * 2048 + k * 1024); } while (0)
; #define PG8_LDB(dst, b, h) do { _Pragma("unroll") for (int n = 0; n < 2; ++n) _Pragma("unroll") for (int k = 0; k < 2; ++k) dst[n][k] = *(const PG8_LAS bf16x8*)(lds + PG8_SB(b, h) + boff + n * 2048 + k * 1024); } while (0)
; #define PG8_MMA(ai, bj, At, Bt) do { __builtin_amdgcn_s_setprio(1); _Pragma("unroll") for (int m = 0; m < 4; ++m) _Pragma("unroll") for (int n = 0; n < 2; ++n) _Pragma("unroll") for (int k = 0; k < 2; ++k) \
;         acc[ai][bj][m][n] = __builtin_amdgcn_mfma_f32_16x16x32_bf16(Bt[n][k], At[m][k], acc[ai][bj][m][n], 0, 0, 0); __builtin_amdgcn_s_setprio(0); } while (0)
; #define PG8_WAIT_V(n) asm volatile("s_waitcnt vmcnt(" #n ")" ::: "memory")
; #define PG8_WAIT_L(n) asm volatile("s_waitcnt lgkmcnt(" #n ")" ::: "memory")
; #define PG8_BAR __builtin_amdgcn_s_barrier()
; #define PG8_SCHED __builtin_amdgcn_sched_barrier(0)
; template <class Epi, class Sched, bool ALIGN_EPI = false, bool SP2 = false>
; __device__ __forceinline__ void gemm_phase(PG8_LAS unsigned char* lds, const Gemm g, const Sched& S, const Epi& E, const int tid_in) {
;     ...
;             PG8_WAIT_V(8); PG8_WAIT_L(0); PG8_BAR; PG8_MMA(1, 0, At, B0); PG8_MMA(1, 1, At, B1); PG8_BAR; PG8_SCHED;
;             PG8_LDB(B0, 1, 0); PG8_LDB(B1, 1, 1); PG8_SCHED; PG8_LDA(At, 1, 0); PG8_STAGE(PG8_SA(0, 1), a2 + hstep, voffA);
;             PG8_WAIT_V(8); PG8_WAIT_L(0); PG8_BAR; PG8_MMA(0, 0, At, B0); PG8_MMA(0, 1, At, B1); PG8_BAR; PG8_SCHED;
	s_setprio 1
	s_waitcnt lgkmcnt(0)
	v_mfma_f32_16x16x32_bf16 v[60:63], v[138:141], v[174:177], 0
	v_mfma_f32_16x16x32_bf16 v[56:59], v[150:153], v[174:177], 0
	v_mfma_f32_16x16x32_bf16 v[44:47], v[138:141], v[182:185], 0
	v_mfma_f32_16x16x32_bf16 v[40:43], v[150:153], v[182:185], 0
	v_mfma_f32_16x16x32_bf16 v[28:31], v[138:141], v[200:203], 0
	v_mfma_f32_16x16x32_bf16 v[24:27], v[150:153], v[200:203], 0
	v_mfma_f32_16x16x32_bf16 v[12:15], v[138:141], v[208:211], 0
	v_mfma_f32_16x16x32_bf16 v[8:11], v[150:153], v[208:211], 0
	v_mfma_f32_16x16x32_bf16 v[60:63], v[146:149], v[178:181], v[60:63]
	v_mfma_f32_16x16x32_bf16 v[56:59], v[154:157], v[178:181], v[56:59]
	v_mfma_f32_16x16x32_bf16 v[44:47], v[146:149], v[186:189], v[44:47]
	v_mfma_f32_16x16x32_bf16 v[40:43], v[154:157], v[186:189], v[40:43]
	v_mfma_f32_16x16x32_bf16 v[28:31], v[146:149], v[204:207], v[28:31]
	v_mfma_f32_16x16x32_bf16 v[24:27], v[154:157], v[204:207], v[24:27]
	v_mfma_f32_16x16x32_bf16 v[12:15], v[146:149], v[212:215], v[12:15]
	v_mfma_f32_16x16x32_bf16 v[8:11], v[154:157], v[212:215], v[8:11]
	s_setprio 0
	s_setprio 1
	v_mfma_f32_16x16x32_bf16 v[52:55], v[158:161], v[174:177], 0
	v_mfma_f32_16x16x32_bf16 v[48:51], v[166:169], v[174:177], 0
	v_mfma_f32_16x16x32_bf16 v[36:39], v[158:161], v[182:185], 0
	v_mfma_f32_16x16x32_bf16 v[32:35], v[166:169], v[182:185], 0
	v_mfma_f32_16x16x32_bf16 v[20:23], v[158:161], v[200:203], 0
	v_mfma_f32_16x16x32_bf16 v[16:19], v[166:169], v[200:203], 0
	v_mfma_f32_16x16x32_bf16 v[4:7], v[158:161], v[208:211], 0
	v_mfma_f32_16x16x32_bf16 v[0:3], v[166:169], v[208:211], 0
	v_mfma_f32_16x16x32_bf16 v[52:55], v[162:165], v[178:181], v[52:55]
	v_mfma_f32_16x16x32_bf16 v[48:51], v[170:173], v[178:181], v[48:51]
	v_mfma_f32_16x16x32_bf16 v[36:39], v[162:165], v[186:189], v[36:39]
	v_mfma_f32_16x16x32_bf16 v[32:35], v[170:173], v[186:189], v[32:35]
	v_mfma_f32_16x16x32_bf16 v[20:23], v[162:165], v[204:207], v[20:23]
	v_mfma_f32_16x16x32_bf16 v[16:19], v[170:173], v[204:207], v[16:19]
	v_mfma_f32_16x16x32_bf16 v[4:7], v[162:165], v[212:215], v[4:7]
	v_mfma_f32_16x16x32_bf16 v[0:3], v[170:173], v[212:215], v[0:3]
	s_setprio 0
	s_barrier
	s_add_i32 s53, 0, 0x18000
	s_add_i32 s54, 0, 0x1c000
	v_add_u32_e32 v154, s53, v143
	v_add_u32_e32 v170, s54, v143
	ds_read_b128 v[138:141], v154
	ds_read_b128 v[146:149], v154 offset:1024
	ds_read_b128 v[150:153], v154 offset:2048
	ds_read_b128 v[154:157], v154 offset:3072
	ds_read_b128 v[158:161], v170
	ds_read_b128 v[162:165], v170 offset:1024
	ds_read_b128 v[166:169], v170 offset:2048
	ds_read_b128 v[170:173], v170 offset:3072
	s_add_u32 s26, s26, s12
	s_addc_u32 s27, s27, 0
	s_mov_b32 m0, s40
	v_lshl_add_u64 v[236:237], s[26:27], 0, v[128:129]
	ds_read_b128 v[174:177], v145 offset:32768
	ds_read_b128 v[178:181], v145 offset:33792
	ds_read_b128 v[182:185], v145 offset:34816
	ds_read_b128 v[186:189], v145 offset:35840
	ds_read_b128 v[200:203], v145 offset:36864
	ds_read_b128 v[204:207], v145 offset:37888
	ds_read_b128 v[208:211], v145 offset:38912
	ds_read_b128 v[212:215], v145 offset:39936
	global_load_lds_dwordx4 v[236:237], off
	v_lshl_add_u64 v[236:237], s[26:27], 0, v[130:131]
	s_mov_b32 m0, s41
	s_nop 0
	global_load_lds_dwordx4 v[236:237], off
	s_waitcnt vmcnt(8)
	s_waitcnt lgkmcnt(0)
	s_barrier
	s_setprio 1
	s_waitcnt lgkmcnt(0)
	v_mfma_f32_16x16x32_bf16 v[124:127], v[138:141], v[174:177], v[124:127]
	v_mfma_f32_16x16x32_bf16 v[120:123], v[150:153], v[174:177], v[120:123]
	v_mfma_f32_16x16x32_bf16 v[108:111], v[138:141], v[182:185], v[108:111]
	v_mfma_f32_16x16x32_bf16 v[104:107], v[150:153], v[182:185], v[104:107]
	v_mfma_f32_16x16x32_bf16 v[92:95], v[138:141], v[200:203], v[92:95]
	v_mfma_f32_16x16x32_bf16 v[88:91], v[150:153], v[200:203], v[88:91]
	v_mfma_f32_16x16x32_bf16 v[76:79], v[138:141], v[208:211], v[76:79]
	v_mfma_f32_16x16x32_bf16 v[72:75], v[150:153], v[208:211], v[72:75]
	v_mfma_f32_16x16x32_bf16 v[124:127], v[146:149], v[178:181], v[124:127]
	v_mfma_f32_16x16x32_bf16 v[120:123], v[154:157], v[178:181], v[120:123]
	v_mfma_f32_16x16x32_bf16 v[108:111], v[146:149], v[186:189], v[108:111]
	v_mfma_f32_16x16x32_bf16 v[104:107], v[154:157], v[186:189], v[104:107]
	v_mfma_f32_16x16x32_bf16 v[92:95], v[146:149], v[204:207], v[92:95]
	v_mfma_f32_16x16x32_bf16 v[88:91], v[154:157], v[204:207], v[88:91]
	v_mfma_f32_16x16x32_bf16 v[76:79], v[146:149], v[212:215], v[76:79]
	v_mfma_f32_16x16x32_bf16 v[72:75], v[154:157], v[212:215], v[72:75]
	s_setprio 0
	s_setprio 1
	v_mfma_f32_16x16x32_bf16 v[116:119], v[158:161], v[174:177], v[116:119]
	v_mfma_f32_16x16x32_bf16 v[112:115], v[166:169], v[174:177], v[112:115]
	v_mfma_f32_16x16x32_bf16 v[100:103], v[158:161], v[182:185], v[100:103]
	v_mfma_f32_16x16x32_bf16 v[96:99], v[166:169], v[182:185], v[96:99]
	v_mfma_f32_16x16x32_bf16 v[84:87], v[158:161], v[200:203], v[84:87]
	v_mfma_f32_16x16x32_bf16 v[80:83], v[166:169], v[200:203], v[80:83]
	v_mfma_f32_16x16x32_bf16 v[68:71], v[158:161], v[208:211], v[68:71]
	v_mfma_f32_16x16x32_bf16 v[64:67], v[166:169], v[208:211], v[64:67]
	v_mfma_f32_16x16x32_bf16 v[116:119], v[162:165], v[178:181], v[116:119]
	v_mfma_f32_16x16x32_bf16 v[112:115], v[170:173], v[178:181], v[112:115]
	v_mfma_f32_16x16x32_bf16 v[100:103], v[162:165], v[186:189], v[100:103]
	v_mfma_f32_16x16x32_bf16 v[96:99], v[170:173], v[186:189], v[96:99]
	v_mfma_f32_16x16x32_bf16 v[84:87], v[162:165], v[204:207], v[84:87]
	v_mfma_f32_16x16x32_bf16 v[80:83], v[170:173], v[204:207], v[80:83]
	v_mfma_f32_16x16x32_bf16 v[68:71], v[162:165], v[212:215], v[68:71]
	v_mfma_f32_16x16x32_bf16 v[64:67], v[170:173], v[212:215], v[64:67]
	s_setprio 0
	s_barrier
; #define PG8_STAGE(bufoff, gbase, voff) do { _Pragma("unroll") for (int _i = 0; _i < 2; ++_i) \
;         __builtin_amdgcn_global_load_lds((const unsigned*)((const char*)(gbase) + (voff)[_i]), (PG8_LAS unsigned*)(lds + (bufoff) + ldsw + _i * 8192), 16, 0, 0); } while (0)
; #define PG8_LDA(dst, b, h) do { _Pragma("unroll") for (int m = 0; m < 4; ++m) _Pragma("unroll") for (int k = 0; k < 2; ++k) dst[m][k] = *(const PG8_LAS bf16x8*)(lds + PG8_SA(b, h) + aoff + m * 2048 + k * 1024); } while (0)
; #define PG8_MMA(ai, bj, At, Bt) do { __builtin_amdgcn_s_setprio(1); _Pragma("unroll") for (int m = 0; m < 4; ++m) _Pragma("unroll") for (int n = 0; n < 2; ++n) _Pragma("unroll") for (int k = 0; k < 2; ++k) \
;         acc[ai][bj][m][n] = __builtin_amdgcn_mfma_f32_16x16x32_bf16(Bt[n][k], At[m][k], acc[ai][bj][m][n], 0, 0, 0); __builtin_amdgcn_s_setprio(0); } while (0)
; #define PG8_WAIT_V(n) asm volatile("s_waitcnt vmcnt(" #n ")" ::: "memory")
; #define PG8_WAIT_L(n) asm volatile("s_waitcnt lgkmcnt(" #n ")" ::: "memory")
; #define PG8_BAR __builtin_amdgcn_s_barrier()
; #define PG8_SCHED __builtin_amdgcn_sched_barrier(0)
; template <class Epi, class Sched, bool ALIGN_EPI = false, bool SP2 = false>
; __device__ __forceinline__ void gemm_phase(PG8_LAS unsigned char* lds, const Gemm g, const Sched& S, const Epi& E, const int tid_in) {
;     ...
;         for (int t = 0; t < nt; t += 2) {
;     ...
;             PG8_LDA(At, 1, 1); PG8_STAGE(PG8_SB(1, 0), b3, voffB); PG8_STAGE(PG8_SB(1, 1), b3 + hstep, voffB); PG8_STAGE(PG8_SA(1, 0), a3, voffA);
;             PG8_WAIT_V(8); PG8_WAIT_L(0); PG8_BAR; PG8_MMA(1, 0, At, B0); PG8_MMA(1, 1, At, B1); PG8_BAR; PG8_SCHED;
	s_add_i32 s26, s53, s35
	v_lshl_add_u64 v[190:191], v[190:191], 0, s[92:93]
	s_mov_b32 m0, s26
	ds_read_b128 v[174:177], v145 offset:49152
	ds_read_b128 v[178:181], v145 offset:50176
	ds_read_b128 v[182:185], v145 offset:51200
	ds_read_b128 v[186:189], v145 offset:52224
	ds_read_b128 v[200:203], v145 offset:53248
	ds_read_b128 v[204:207], v145 offset:54272
	ds_read_b128 v[208:211], v145 offset:55296
	ds_read_b128 v[212:215], v145 offset:56320
	global_load_lds_dwordx4 v[190:191], off
	v_lshl_add_u64 v[190:191], v[218:219], 0, s[92:93]
	s_add_i32 m0, s26, 0x2000
	s_add_i32 s26, s54, s35
	global_load_lds_dwordx4 v[190:191], off
	v_lshl_add_u64 v[190:191], v[220:221], 0, s[92:93]
	s_mov_b32 m0, s26
	s_nop 0
	global_load_lds_dwordx4 v[190:191], off
	v_lshl_add_u64 v[190:191], v[230:231], 0, s[92:93]
	s_add_i32 m0, s26, 0x2000
	s_nop 0
	global_load_lds_dwordx4 v[190:191], off
	v_lshl_add_u64 v[190:191], v[232:233], 0, s[92:93]
	s_mov_b32 m0, s42
	s_nop 0
	global_load_lds_dwordx4 v[190:191], off
	v_lshl_add_u64 v[190:191], v[234:235], 0, s[92:93]
	s_mov_b32 m0, s43
	s_nop 0
	global_load_lds_dwordx4 v[190:191], off
	s_waitcnt vmcnt(8)
	s_waitcnt lgkmcnt(0)
	s_barrier
	s_setprio 1
	s_waitcnt lgkmcnt(0)
	v_mfma_f32_16x16x32_bf16 v[60:63], v[138:141], v[174:177], v[60:63]
	v_mfma_f32_16x16x32_bf16 v[56:59], v[150:153], v[174:177], v[56:59]
	v_mfma_f32_16x16x32_bf16 v[44:47], v[138:141], v[182:185], v[44:47]
	v_mfma_f32_16x16x32_bf16 v[40:43], v[150:153], v[182:185], v[40:43]
	v_mfma_f32_16x16x32_bf16 v[28:31], v[138:141], v[200:203], v[28:31]
	v_mfma_f32_16x16x32_bf16 v[24:27], v[150:153], v[200:203], v[24:27]
	v_mfma_f32_16x16x32_bf16 v[12:15], v[138:141], v[208:211], v[12:15]
	v_mfma_f32_16x16x32_bf16 v[8:11], v[150:153], v[208:211], v[8:11]
	v_mfma_f32_16x16x32_bf16 v[60:63], v[146:149], v[178:181], v[60:63]
	v_mfma_f32_16x16x32_bf16 v[56:59], v[154:157], v[178:181], v[56:59]
	v_mfma_f32_16x16x32_bf16 v[44:47], v[146:149], v[186:189], v[44:47]
	v_mfma_f32_16x16x32_bf16 v[40:43], v[154:157], v[186:189], v[40:43]
	v_mfma_f32_16x16x32_bf16 v[28:31], v[146:149], v[204:207], v[28:31]
	v_mfma_f32_16x16x32_bf16 v[24:27], v[154:157], v[204:207], v[24:27]
	v_mfma_f32_16x16x32_bf16 v[12:15], v[146:149], v[212:215], v[12:15]
	v_mfma_f32_16x16x32_bf16 v[8:11], v[154:157], v[212:215], v[8:11]
	s_setprio 0
	s_setprio 1
	v_mfma_f32_16x16x32_bf16 v[52:55], v[158:161], v[174:177], v[52:55]
	v_mfma_f32_16x16x32_bf16 v[48:51], v[166:169], v[174:177], v[48:51]
	v_mfma_f32_16x16x32_bf16 v[36:39], v[158:161], v[182:185], v[36:39]
	v_mfma_f32_16x16x32_bf16 v[32:35], v[166:169], v[182:185], v[32:35]
	v_mfma_f32_16x16x32_bf16 v[20:23], v[158:161], v[200:203], v[20:23]
	v_mfma_f32_16x16x32_bf16 v[16:19], v[166:169], v[200:203], v[16:19]
	v_mfma_f32_16x16x32_bf16 v[4:7], v[158:161], v[208:211], v[4:7]
	v_mfma_f32_16x16x32_bf16 v[0:3], v[166:169], v[208:211], v[0:3]
	v_mfma_f32_16x16x32_bf16 v[52:55], v[162:165], v[178:181], v[52:55]
	v_mfma_f32_16x16x32_bf16 v[48:51], v[170:173], v[178:181], v[48:51]
	v_mfma_f32_16x16x32_bf16 v[36:39], v[162:165], v[186:189], v[36:39]
	v_mfma_f32_16x16x32_bf16 v[32:35], v[170:173], v[186:189], v[32:35]
	v_mfma_f32_16x16x32_bf16 v[20:23], v[162:165], v[204:207], v[20:23]
	v_mfma_f32_16x16x32_bf16 v[16:19], v[170:173], v[204:207], v[16:19]
	v_mfma_f32_16x16x32_bf16 v[4:7], v[162:165], v[212:215], v[4:7]
	v_mfma_f32_16x16x32_bf16 v[0:3], v[170:173], v[212:215], v[0:3]
	s_setprio 0
	s_barrier
	s_add_u32 s24, s24, 0x100
	s_addc_u32 s25, s25, 0
	s_add_u32 s29, s29, 0x100
	s_addc_u32 s51, s51, 0
	s_cmp_ge_u32 s52, s50
	s_mov_b32 s26, s52
	s_cbranch_scc0 .LBB0_284
	s_branch gk284_exit

; #define PG8_BAR __builtin_amdgcn_s_barrier()
; template <class Epi, class Sched, bool ALIGN_EPI = false, bool SP2 = false>
; __device__ __forceinline__ void gemm_phase(PG8_LAS unsigned char* lds, const Gemm g, const Sched& S, const Epi& E, const int tid_in) {
;     ...
;         if constexpr (ALIGN_EPI) { if (wr == 0) PG8_BAR; }
gk284_exit:
	s_and_b64 vcc, exec, s[16:17]
	s_cbranch_vccz .LBB0_287
